# same as v68 but the residual epilogue keeps one wait state after every packed f32 op (compiler convention); no other change
# baseline (speedup 1.0000x reference)
; #define LAS __attribute__((address_space(3)))
; __device__ __forceinline__ unsigned cvt_pk_bf16(float lo, float hi) { unsigned r; asm volatile("v_cvt_pk_bf16_f32 %0, %1, %2" : "=v"(r) : "v"(lo), "v"(hi)); return r; }
; __device__ __forceinline__ u32x4 zero_frag() { unsigned z_ = 0u; asm volatile("" : "+v"(z_)); return (u32x4){z_, z_, z_, z_}; }
; __device__ __forceinline__ void epi_lane(int& fr, int& fq) { unsigned ones = ~0u; asm volatile("" : "+s"(ones)); const int ln = (int)__builtin_amdgcn_mbcnt_hi(ones, __builtin_amdgcn_mbcnt_lo(ones, 0u)); fr = ln & 15; fq = ln >> 4; }
;     __device__ __forceinline__ void operator()(f32x4 (&acc)[2][2][4][2], const Unit& u, int wr, int wc, LAS unsigned char* lds, int& rs_pm) const {
;         int fr, fq; epi_lane(fr, fq);
;         const int row0 = u.pm * BM + wr * 64 + fr, col0 = u.pn * BM + wc * 32 + 8 * fq; u32x4 zb = zero_frag();
; #pragma unroll
;         for (int ai = 0; ai < 2; ++ai)
; #pragma unroll
;             for (int m = 0; m < 4; ++m) { float ss = 0.f;
;                 bf16* const xrow = xb + (((size_t)(u.pm * 32 + u.pn * 4 + (wc >> 1)) * BM + (wr * 64 + fr + ai * HALF + m * 16)) * 64 + (wc & 1) * 32 + 8 * fq);
; #pragma unroll
;                 for (int bj = 0; bj < 2; ++bj) {
;                     const u32x4 xw = *(const u32x4*)(xrow + (size_t)bj * (2 * BM * 64));
;                     const f32x4 x0 = (f32x4){bflo(xw.x), bfhi(xw.x), bflo(xw.y), bfhi(xw.y)}, x1 = (f32x4){bflo(xw.z), bfhi(xw.z), bflo(xw.w), bfhi(xw.w)};
;                     const f32x4 v0 = x0 + acc[ai][bj][m][0] * alpha, v1 = x1 + acc[ai][bj][m][1] * alpha; zero_acc(acc[ai][bj][m][0], zb); zero_acc(acc[ai][bj][m][1], zb);
;                     ss += (v0[0] * v0[0] + v0[1] * v0[1]) + (v0[2] * v0[2] + v0[3] * v0[3]) + (v1[0] * v1[0] + v1[1] * v1[1]) + (v1[2] * v1[2] + v1[3] * v1[3]);
;                     u32x4 w; w.x = cvt_pk_bf16(v0[0], v0[1]); w.y = cvt_pk_bf16(v0[2], v0[3]); w.z = cvt_pk_bf16(v1[0], v1[1]); w.w = cvt_pk_bf16(v1[2], v1[3]);
;                     *(u32x4*)(xrow + (size_t)bj * (2 * BM * 64)) = w; }
.LBB0_297:
	v_mov_b32_e32 v132, v1
	v_mov_b32_e32 v133, v1
	v_mov_b32_e32 v134, v1
	v_mov_b32_e32 v135, v1
	v_xor_b32_e32 v174, 16, v238
	v_xor_b32_e32 v175, 32, v238
	v_lshlrev_b32_e32 v174, 2, v174
	v_lshlrev_b32_e32 v175, 2, v175
	s_waitcnt vmcnt(7)
	v_lshlrev_b32_e32 v156, 16, v176
	v_and_b32_e32 v157, 0xffff0000, v176
	v_lshlrev_b32_e32 v158, 16, v177
	v_and_b32_e32 v159, 0xffff0000, v177
	v_lshlrev_b32_e32 v160, 16, v178
	v_and_b32_e32 v161, 0xffff0000, v178
	v_lshlrev_b32_e32 v162, 16, v179
	v_and_b32_e32 v163, 0xffff0000, v179
	v_pk_fma_f32 v[156:157], v[8:9], 0.5, v[156:157] op_sel_hi:[1,0,1]
	v_pk_fma_f32 v[158:159], v[10:11], 0.5, v[158:159] op_sel_hi:[1,0,1]
	v_pk_fma_f32 v[160:161], v[56:57], 0.5, v[160:161] op_sel_hi:[1,0,1]
	v_pk_fma_f32 v[162:163], v[58:59], 0.5, v[162:163] op_sel_hi:[1,0,1]
	v_pk_mul_f32 v[164:165], v[156:157], v[156:157]
	v_cvt_pk_bf16_f32 v176, v156, v157
	v_pk_fma_f32 v[164:165], v[158:159], v[158:159], v[164:165]
	v_cvt_pk_bf16_f32 v177, v158, v159
	v_pk_fma_f32 v[164:165], v[160:161], v[160:161], v[164:165]
	v_cvt_pk_bf16_f32 v178, v160, v161
	v_pk_fma_f32 v[164:165], v[162:163], v[162:163], v[164:165]
	v_cvt_pk_bf16_f32 v179, v162, v163
	v_mfma_f32_16x16x32_bf16 v[8:11], v[132:135], v[132:135], 0
	v_mfma_f32_16x16x32_bf16 v[56:59], v[132:135], v[132:135], 0
	global_store_dwordx4 v222, v[176:179], s[98:99]
	s_nop 0
	s_add_u32 s100, s98, 0x4000
	s_addc_u32 s101, s99, 0
	global_load_dwordx4 v[176:179], v222, s[100:101]
	s_waitcnt vmcnt(8)
	v_lshlrev_b32_e32 v156, 16, v180
	v_and_b32_e32 v157, 0xffff0000, v180
	v_lshlrev_b32_e32 v158, 16, v181
	v_and_b32_e32 v159, 0xffff0000, v181
	v_lshlrev_b32_e32 v160, 16, v182
	v_and_b32_e32 v161, 0xffff0000, v182
	v_lshlrev_b32_e32 v162, 16, v183
	v_and_b32_e32 v163, 0xffff0000, v183
	v_pk_fma_f32 v[156:157], v[4:5], 0.5, v[156:157] op_sel_hi:[1,0,1]
	v_pk_fma_f32 v[158:159], v[6:7], 0.5, v[158:159] op_sel_hi:[1,0,1]
	v_pk_fma_f32 v[160:161], v[28:29], 0.5, v[160:161] op_sel_hi:[1,0,1]
	v_pk_fma_f32 v[162:163], v[30:31], 0.5, v[162:163] op_sel_hi:[1,0,1]
	v_pk_fma_f32 v[164:165], v[156:157], v[156:157], v[164:165]
	v_cvt_pk_bf16_f32 v180, v156, v157
	v_pk_fma_f32 v[164:165], v[158:159], v[158:159], v[164:165]
	v_cvt_pk_bf16_f32 v181, v158, v159
	v_pk_fma_f32 v[164:165], v[160:161], v[160:161], v[164:165]
	v_cvt_pk_bf16_f32 v182, v160, v161
	v_pk_fma_f32 v[164:165], v[162:163], v[162:163], v[164:165]
	v_cvt_pk_bf16_f32 v183, v162, v163
	v_mfma_f32_16x16x32_bf16 v[4:7], v[132:135], v[132:135], 0
	v_mfma_f32_16x16x32_bf16 v[28:31], v[132:135], v[132:135], 0
	s_add_u32 s100, s98, 0x10000
	s_addc_u32 s101, s99, 0
	global_store_dwordx4 v222, v[180:183], s[100:101]
	v_add_f32_e32 v166, v164, v165
	s_add_u32 s100, s98, 0x14000
	s_addc_u32 s101, s99, 0
	global_load_dwordx4 v[180:183], v222, s[100:101]
	s_waitcnt vmcnt(9)
	v_lshlrev_b32_e32 v156, 16, v184
	v_and_b32_e32 v157, 0xffff0000, v184
	v_lshlrev_b32_e32 v158, 16, v185
	v_and_b32_e32 v159, 0xffff0000, v185
	v_lshlrev_b32_e32 v160, 16, v186
	v_and_b32_e32 v161, 0xffff0000, v186
	v_lshlrev_b32_e32 v162, 16, v187
	v_and_b32_e32 v163, 0xffff0000, v187
	v_pk_fma_f32 v[156:157], v[52:53], 0.5, v[156:157] op_sel_hi:[1,0,1]
	v_pk_fma_f32 v[158:159], v[54:55], 0.5, v[158:159] op_sel_hi:[1,0,1]
	v_pk_fma_f32 v[160:161], v[48:49], 0.5, v[160:161] op_sel_hi:[1,0,1]
	v_pk_fma_f32 v[162:163], v[50:51], 0.5, v[162:163] op_sel_hi:[1,0,1]
	v_pk_mul_f32 v[164:165], v[156:157], v[156:157]
	v_cvt_pk_bf16_f32 v184, v156, v157
	v_pk_fma_f32 v[164:165], v[158:159], v[158:159], v[164:165]
	v_cvt_pk_bf16_f32 v185, v158, v159
	v_pk_fma_f32 v[164:165], v[160:161], v[160:161], v[164:165]
	v_cvt_pk_bf16_f32 v186, v160, v161
	v_pk_fma_f32 v[164:165], v[162:163], v[162:163], v[164:165]
	v_cvt_pk_bf16_f32 v187, v162, v163
	v_mfma_f32_16x16x32_bf16 v[52:55], v[132:135], v[132:135], 0
	v_mfma_f32_16x16x32_bf16 v[48:51], v[132:135], v[132:135], 0
	global_store_dwordx4 v222, v[184:187], s[98:99] offset:2048
	s_nop 0
	s_add_u32 s100, s98, 0x4000
	s_addc_u32 s101, s99, 0
	global_load_dwordx4 v[184:187], v222, s[100:101] offset:2048
	s_waitcnt vmcnt(10)
	v_lshlrev_b32_e32 v156, 16, v188
	v_and_b32_e32 v157, 0xffff0000, v188
	v_lshlrev_b32_e32 v158, 16, v189
	v_and_b32_e32 v159, 0xffff0000, v189
	v_lshlrev_b32_e32 v160, 16, v190
	v_and_b32_e32 v161, 0xffff0000, v190
	v_lshlrev_b32_e32 v162, 16, v191
	v_and_b32_e32 v163, 0xffff0000, v191
	v_pk_fma_f32 v[156:157], v[96:97], 0.5, v[156:157] op_sel_hi:[1,0,1]
	v_pk_fma_f32 v[158:159], v[98:99], 0.5, v[158:159] op_sel_hi:[1,0,1]
	v_pk_fma_f32 v[160:161], v[92:93], 0.5, v[160:161] op_sel_hi:[1,0,1]
	v_pk_fma_f32 v[162:163], v[94:95], 0.5, v[162:163] op_sel_hi:[1,0,1]
	v_pk_fma_f32 v[164:165], v[156:157], v[156:157], v[164:165]
	v_cvt_pk_bf16_f32 v188, v156, v157
	v_pk_fma_f32 v[164:165], v[158:159], v[158:159], v[164:165]
	v_cvt_pk_bf16_f32 v189, v158, v159
	v_pk_fma_f32 v[164:165], v[160:161], v[160:161], v[164:165]
	v_cvt_pk_bf16_f32 v190, v160, v161
	v_pk_fma_f32 v[164:165], v[162:163], v[162:163], v[164:165]
	v_cvt_pk_bf16_f32 v191, v162, v163
	v_mfma_f32_16x16x32_bf16 v[96:99], v[132:135], v[132:135], 0
	v_mfma_f32_16x16x32_bf16 v[92:95], v[132:135], v[132:135], 0
	s_add_u32 s100, s98, 0x10000
	s_addc_u32 s101, s99, 0
	global_store_dwordx4 v222, v[188:191], s[100:101] offset:2048
	v_add_f32_e32 v167, v164, v165
	s_add_u32 s100, s98, 0x14000
	s_addc_u32 s101, s99, 0
	global_load_dwordx4 v[188:191], v222, s[100:101] offset:2048
	s_waitcnt vmcnt(11)
; __device__ __forceinline__ unsigned cvt_pk_bf16(float lo, float hi) { unsigned r; asm volatile("v_cvt_pk_bf16_f32 %0, %1, %2" : "=v"(r) : "v"(lo), "v"(hi)); return r; }
;     __device__ __forceinline__ void operator()(f32x4 (&acc)[2][2][4][2], const Unit& u, int wr, int wc, LAS unsigned char* lds, int& rs_pm) const {
;     ...
;             for (int m = 0; m < 4; ++m) { float ss = 0.f;
;                 bf16* const xrow = xb + (((size_t)(u.pm * 32 + u.pn * 4 + (wc >> 1)) * BM + (wr * 64 + fr + ai * HALF + m * 16)) * 64 + (wc & 1) * 32 + 8 * fq);
; #pragma unroll
;                 for (int bj = 0; bj < 2; ++bj) {
;                     const u32x4 xw = *(const u32x4*)(xrow + (size_t)bj * (2 * BM * 64));
;                     const f32x4 x0 = (f32x4){bflo(xw.x), bfhi(xw.x), bflo(xw.y), bfhi(xw.y)}, x1 = (f32x4){bflo(xw.z), bfhi(xw.z), bflo(xw.w), bfhi(xw.w)};
;                     const f32x4 v0 = x0 + acc[ai][bj][m][0] * alpha, v1 = x1 + acc[ai][bj][m][1] * alpha; zero_acc(acc[ai][bj][m][0], zb); zero_acc(acc[ai][bj][m][1], zb);
;                     ss += (v0[0] * v0[0] + v0[1] * v0[1]) + (v0[2] * v0[2] + v0[3] * v0[3]) + (v1[0] * v1[0] + v1[1] * v1[1]) + (v1[2] * v1[2] + v1[3] * v1[3]);
;                     u32x4 w; w.x = cvt_pk_bf16(v0[0], v0[1]); w.y = cvt_pk_bf16(v0[2], v0[3]); w.z = cvt_pk_bf16(v1[0], v1[1]); w.w = cvt_pk_bf16(v1[2], v1[3]);
;                     *(u32x4*)(xrow + (size_t)bj * (2 * BM * 64)) = w; }
	v_lshlrev_b32_e32 v156, 16, v192
	v_and_b32_e32 v157, 0xffff0000, v192
	v_lshlrev_b32_e32 v158, 16, v193
	v_and_b32_e32 v159, 0xffff0000, v193
	v_lshlrev_b32_e32 v160, 16, v194
	v_and_b32_e32 v161, 0xffff0000, v194
	v_lshlrev_b32_e32 v162, 16, v195
	v_and_b32_e32 v163, 0xffff0000, v195
	v_pk_fma_f32 v[156:157], v[44:45], 0.5, v[156:157] op_sel_hi:[1,0,1]
	v_pk_fma_f32 v[158:159], v[46:47], 0.5, v[158:159] op_sel_hi:[1,0,1]
	v_pk_fma_f32 v[160:161], v[40:41], 0.5, v[160:161] op_sel_hi:[1,0,1]
	v_pk_fma_f32 v[162:163], v[42:43], 0.5, v[162:163] op_sel_hi:[1,0,1]
	v_pk_mul_f32 v[164:165], v[156:157], v[156:157]
	v_cvt_pk_bf16_f32 v192, v156, v157
	v_pk_fma_f32 v[164:165], v[158:159], v[158:159], v[164:165]
	v_cvt_pk_bf16_f32 v193, v158, v159
	v_pk_fma_f32 v[164:165], v[160:161], v[160:161], v[164:165]
	v_cvt_pk_bf16_f32 v194, v160, v161
	v_pk_fma_f32 v[164:165], v[162:163], v[162:163], v[164:165]
	v_cvt_pk_bf16_f32 v195, v162, v163
	v_mfma_f32_16x16x32_bf16 v[44:47], v[132:135], v[132:135], 0
	v_mfma_f32_16x16x32_bf16 v[40:43], v[132:135], v[132:135], 0
	s_add_u32 s100, s98, 0x1000
	s_addc_u32 s101, s99, 0
	global_store_dwordx4 v222, v[192:195], s[100:101]
	s_nop 0
	s_add_u32 s100, s98, 0x5000
	s_addc_u32 s101, s99, 0
	global_load_dwordx4 v[192:195], v222, s[100:101]
	s_waitcnt vmcnt(12)
	v_lshlrev_b32_e32 v156, 16, v196
	v_and_b32_e32 v157, 0xffff0000, v196
	v_lshlrev_b32_e32 v158, 16, v197
	v_and_b32_e32 v159, 0xffff0000, v197
	v_lshlrev_b32_e32 v160, 16, v198
	v_and_b32_e32 v161, 0xffff0000, v198
	v_lshlrev_b32_e32 v162, 16, v199
	v_and_b32_e32 v163, 0xffff0000, v199
	v_pk_fma_f32 v[156:157], v[88:89], 0.5, v[156:157] op_sel_hi:[1,0,1]
	v_pk_fma_f32 v[158:159], v[90:91], 0.5, v[158:159] op_sel_hi:[1,0,1]
	v_pk_fma_f32 v[160:161], v[84:85], 0.5, v[160:161] op_sel_hi:[1,0,1]
	v_pk_fma_f32 v[162:163], v[86:87], 0.5, v[162:163] op_sel_hi:[1,0,1]
	v_pk_fma_f32 v[164:165], v[156:157], v[156:157], v[164:165]
	v_cvt_pk_bf16_f32 v196, v156, v157
	v_pk_fma_f32 v[164:165], v[158:159], v[158:159], v[164:165]
	v_cvt_pk_bf16_f32 v197, v158, v159
	v_pk_fma_f32 v[164:165], v[160:161], v[160:161], v[164:165]
	v_cvt_pk_bf16_f32 v198, v160, v161
	v_pk_fma_f32 v[164:165], v[162:163], v[162:163], v[164:165]
	v_cvt_pk_bf16_f32 v199, v162, v163
	v_mfma_f32_16x16x32_bf16 v[88:91], v[132:135], v[132:135], 0
	v_mfma_f32_16x16x32_bf16 v[84:87], v[132:135], v[132:135], 0
	s_add_u32 s100, s98, 0x11000
	s_addc_u32 s101, s99, 0
	global_store_dwordx4 v222, v[196:199], s[100:101]
	v_add_f32_e32 v168, v164, v165
	s_add_u32 s100, s98, 0x15000
	s_addc_u32 s101, s99, 0
	global_load_dwordx4 v[196:199], v222, s[100:101]
	s_waitcnt vmcnt(13)
	v_lshlrev_b32_e32 v156, 16, v214
	v_and_b32_e32 v157, 0xffff0000, v214
	v_lshlrev_b32_e32 v158, 16, v215
	v_and_b32_e32 v159, 0xffff0000, v215
	v_lshlrev_b32_e32 v160, 16, v216
	v_and_b32_e32 v161, 0xffff0000, v216
	v_lshlrev_b32_e32 v162, 16, v217
	v_and_b32_e32 v163, 0xffff0000, v217
	v_pk_fma_f32 v[156:157], v[36:37], 0.5, v[156:157] op_sel_hi:[1,0,1]
	v_pk_fma_f32 v[158:159], v[38:39], 0.5, v[158:159] op_sel_hi:[1,0,1]
	v_pk_fma_f32 v[160:161], v[32:33], 0.5, v[160:161] op_sel_hi:[1,0,1]
	v_pk_fma_f32 v[162:163], v[34:35], 0.5, v[162:163] op_sel_hi:[1,0,1]
	v_pk_mul_f32 v[164:165], v[156:157], v[156:157]
	v_cvt_pk_bf16_f32 v214, v156, v157
	v_pk_fma_f32 v[164:165], v[158:159], v[158:159], v[164:165]
	v_cvt_pk_bf16_f32 v215, v158, v159
	v_pk_fma_f32 v[164:165], v[160:161], v[160:161], v[164:165]
	v_cvt_pk_bf16_f32 v216, v160, v161
	v_pk_fma_f32 v[164:165], v[162:163], v[162:163], v[164:165]
	v_cvt_pk_bf16_f32 v217, v162, v163
	v_mfma_f32_16x16x32_bf16 v[36:39], v[132:135], v[132:135], 0
	v_mfma_f32_16x16x32_bf16 v[32:35], v[132:135], v[132:135], 0
	s_add_u32 s100, s98, 0x1000
	s_addc_u32 s101, s99, 0
	global_store_dwordx4 v222, v[214:217], s[100:101] offset:2048
	s_nop 0
	s_add_u32 s100, s98, 0x5000
	s_addc_u32 s101, s99, 0
	global_load_dwordx4 v[214:217], v222, s[100:101] offset:2048
	s_waitcnt vmcnt(14)
	v_lshlrev_b32_e32 v156, 16, v218
	v_and_b32_e32 v157, 0xffff0000, v218
	v_lshlrev_b32_e32 v158, 16, v219
	v_and_b32_e32 v159, 0xffff0000, v219
	v_lshlrev_b32_e32 v160, 16, v220
	v_and_b32_e32 v161, 0xffff0000, v220
	v_lshlrev_b32_e32 v162, 16, v221
	v_and_b32_e32 v163, 0xffff0000, v221
	v_pk_fma_f32 v[156:157], v[80:81], 0.5, v[156:157] op_sel_hi:[1,0,1]
	v_pk_fma_f32 v[158:159], v[82:83], 0.5, v[158:159] op_sel_hi:[1,0,1]
	v_pk_fma_f32 v[160:161], v[76:77], 0.5, v[160:161] op_sel_hi:[1,0,1]
	v_pk_fma_f32 v[162:163], v[78:79], 0.5, v[162:163] op_sel_hi:[1,0,1]
	v_pk_fma_f32 v[164:165], v[156:157], v[156:157], v[164:165]
	v_cvt_pk_bf16_f32 v218, v156, v157
	v_pk_fma_f32 v[164:165], v[158:159], v[158:159], v[164:165]
	v_cvt_pk_bf16_f32 v219, v158, v159
	v_pk_fma_f32 v[164:165], v[160:161], v[160:161], v[164:165]
	v_cvt_pk_bf16_f32 v220, v160, v161
	v_pk_fma_f32 v[164:165], v[162:163], v[162:163], v[164:165]
	v_cvt_pk_bf16_f32 v221, v162, v163
	v_mfma_f32_16x16x32_bf16 v[80:83], v[132:135], v[132:135], 0
	v_mfma_f32_16x16x32_bf16 v[76:79], v[132:135], v[132:135], 0
	s_add_u32 s100, s98, 0x11000
	s_addc_u32 s101, s99, 0
	global_store_dwordx4 v222, v[218:221], s[100:101] offset:2048
	v_add_f32_e32 v169, v164, v165
	s_add_u32 s100, s98, 0x15000
	s_addc_u32 s101, s99, 0
	global_load_dwordx4 v[218:221], v222, s[100:101] offset:2048
	s_waitcnt vmcnt(14)
; __device__ __forceinline__ unsigned cvt_pk_bf16(float lo, float hi) { unsigned r; asm volatile("v_cvt_pk_bf16_f32 %0, %1, %2" : "=v"(r) : "v"(lo), "v"(hi)); return r; }
;     __device__ __forceinline__ void operator()(f32x4 (&acc)[2][2][4][2], const Unit& u, int wr, int wc, LAS unsigned char* lds, int& rs_pm) const {
;     ...
;             for (int m = 0; m < 4; ++m) { float ss = 0.f;
;                 bf16* const xrow = xb + (((size_t)(u.pm * 32 + u.pn * 4 + (wc >> 1)) * BM + (wr * 64 + fr + ai * HALF + m * 16)) * 64 + (wc & 1) * 32 + 8 * fq);
; #pragma unroll
;                 for (int bj = 0; bj < 2; ++bj) {
;                     const u32x4 xw = *(const u32x4*)(xrow + (size_t)bj * (2 * BM * 64));
;                     const f32x4 x0 = (f32x4){bflo(xw.x), bfhi(xw.x), bflo(xw.y), bfhi(xw.y)}, x1 = (f32x4){bflo(xw.z), bfhi(xw.z), bflo(xw.w), bfhi(xw.w)};
;                     const f32x4 v0 = x0 + acc[ai][bj][m][0] * alpha, v1 = x1 + acc[ai][bj][m][1] * alpha; zero_acc(acc[ai][bj][m][0], zb); zero_acc(acc[ai][bj][m][1], zb);
;                     ss += (v0[0] * v0[0] + v0[1] * v0[1]) + (v0[2] * v0[2] + v0[3] * v0[3]) + (v1[0] * v1[0] + v1[1] * v1[1]) + (v1[2] * v1[2] + v1[3] * v1[3]);
;                     u32x4 w; w.x = cvt_pk_bf16(v0[0], v0[1]); w.y = cvt_pk_bf16(v0[2], v0[3]); w.z = cvt_pk_bf16(v1[0], v1[1]); w.w = cvt_pk_bf16(v1[2], v1[3]);
;                     *(u32x4*)(xrow + (size_t)bj * (2 * BM * 64)) = w; }
	v_lshlrev_b32_e32 v156, 16, v176
	v_and_b32_e32 v157, 0xffff0000, v176
	v_lshlrev_b32_e32 v158, 16, v177
	v_and_b32_e32 v159, 0xffff0000, v177
	v_lshlrev_b32_e32 v160, 16, v178
	v_and_b32_e32 v161, 0xffff0000, v178
	v_lshlrev_b32_e32 v162, 16, v179
	v_and_b32_e32 v163, 0xffff0000, v179
	v_pk_fma_f32 v[156:157], v[24:25], 0.5, v[156:157] op_sel_hi:[1,0,1]
	v_pk_fma_f32 v[158:159], v[26:27], 0.5, v[158:159] op_sel_hi:[1,0,1]
	v_pk_fma_f32 v[160:161], v[20:21], 0.5, v[160:161] op_sel_hi:[1,0,1]
	v_pk_fma_f32 v[162:163], v[22:23], 0.5, v[162:163] op_sel_hi:[1,0,1]
	v_pk_mul_f32 v[164:165], v[156:157], v[156:157]
	v_cvt_pk_bf16_f32 v176, v156, v157
	v_pk_fma_f32 v[164:165], v[158:159], v[158:159], v[164:165]
	v_cvt_pk_bf16_f32 v177, v158, v159
	v_pk_fma_f32 v[164:165], v[160:161], v[160:161], v[164:165]
	v_cvt_pk_bf16_f32 v178, v160, v161
	v_pk_fma_f32 v[164:165], v[162:163], v[162:163], v[164:165]
	v_cvt_pk_bf16_f32 v179, v162, v163
	v_mfma_f32_16x16x32_bf16 v[24:27], v[132:135], v[132:135], 0
	v_mfma_f32_16x16x32_bf16 v[20:23], v[132:135], v[132:135], 0
	s_add_u32 s100, s98, 0x4000
	s_addc_u32 s101, s99, 0
	global_store_dwordx4 v222, v[176:179], s[100:101]
	s_nop 0
	s_waitcnt vmcnt(13)
	v_lshlrev_b32_e32 v156, 16, v180
	v_and_b32_e32 v157, 0xffff0000, v180
	v_lshlrev_b32_e32 v158, 16, v181
	v_and_b32_e32 v159, 0xffff0000, v181
	v_lshlrev_b32_e32 v160, 16, v182
	v_and_b32_e32 v161, 0xffff0000, v182
	v_lshlrev_b32_e32 v162, 16, v183
	v_and_b32_e32 v163, 0xffff0000, v183
	v_pk_fma_f32 v[156:157], v[128:129], 0.5, v[156:157] op_sel_hi:[1,0,1]
	v_pk_fma_f32 v[158:159], v[130:131], 0.5, v[158:159] op_sel_hi:[1,0,1]
	v_pk_fma_f32 v[160:161], v[124:125], 0.5, v[160:161] op_sel_hi:[1,0,1]
	v_pk_fma_f32 v[162:163], v[126:127], 0.5, v[162:163] op_sel_hi:[1,0,1]
	v_pk_fma_f32 v[164:165], v[156:157], v[156:157], v[164:165]
	v_cvt_pk_bf16_f32 v180, v156, v157
	v_pk_fma_f32 v[164:165], v[158:159], v[158:159], v[164:165]
	v_cvt_pk_bf16_f32 v181, v158, v159
	v_pk_fma_f32 v[164:165], v[160:161], v[160:161], v[164:165]
	v_cvt_pk_bf16_f32 v182, v160, v161
	v_pk_fma_f32 v[164:165], v[162:163], v[162:163], v[164:165]
	v_cvt_pk_bf16_f32 v183, v162, v163
	v_mfma_f32_16x16x32_bf16 v[128:131], v[132:135], v[132:135], 0
	v_mfma_f32_16x16x32_bf16 v[124:127], v[132:135], v[132:135], 0
	s_add_u32 s100, s98, 0x14000
	s_addc_u32 s101, s99, 0
	global_store_dwordx4 v222, v[180:183], s[100:101]
	v_add_f32_e32 v170, v164, v165
	s_waitcnt vmcnt(12)
	v_lshlrev_b32_e32 v156, 16, v184
	v_and_b32_e32 v157, 0xffff0000, v184
	v_lshlrev_b32_e32 v158, 16, v185
	v_and_b32_e32 v159, 0xffff0000, v185
	v_lshlrev_b32_e32 v160, 16, v186
	v_and_b32_e32 v161, 0xffff0000, v186
	v_lshlrev_b32_e32 v162, 16, v187
	v_and_b32_e32 v163, 0xffff0000, v187
	v_pk_fma_f32 v[156:157], v[64:65], 0.5, v[156:157] op_sel_hi:[1,0,1]
	v_pk_fma_f32 v[158:159], v[66:67], 0.5, v[158:159] op_sel_hi:[1,0,1]
	v_pk_fma_f32 v[160:161], v[72:73], 0.5, v[160:161] op_sel_hi:[1,0,1]
	v_pk_fma_f32 v[162:163], v[74:75], 0.5, v[162:163] op_sel_hi:[1,0,1]
	v_pk_mul_f32 v[164:165], v[156:157], v[156:157]
	v_cvt_pk_bf16_f32 v184, v156, v157
	v_pk_fma_f32 v[164:165], v[158:159], v[158:159], v[164:165]
	v_cvt_pk_bf16_f32 v185, v158, v159
	v_pk_fma_f32 v[164:165], v[160:161], v[160:161], v[164:165]
	v_cvt_pk_bf16_f32 v186, v160, v161
	v_pk_fma_f32 v[164:165], v[162:163], v[162:163], v[164:165]
	v_cvt_pk_bf16_f32 v187, v162, v163
	v_mfma_f32_16x16x32_bf16 v[64:67], v[132:135], v[132:135], 0
	v_mfma_f32_16x16x32_bf16 v[72:75], v[132:135], v[132:135], 0
	s_add_u32 s100, s98, 0x4000
	s_addc_u32 s101, s99, 0
	global_store_dwordx4 v222, v[184:187], s[100:101] offset:2048
	s_nop 0
	s_waitcnt vmcnt(11)
	v_lshlrev_b32_e32 v156, 16, v188
	v_and_b32_e32 v157, 0xffff0000, v188
	v_lshlrev_b32_e32 v158, 16, v189
	v_and_b32_e32 v159, 0xffff0000, v189
	v_lshlrev_b32_e32 v160, 16, v190
	v_and_b32_e32 v161, 0xffff0000, v190
	v_lshlrev_b32_e32 v162, 16, v191
	v_and_b32_e32 v163, 0xffff0000, v191
	v_pk_fma_f32 v[156:157], v[120:121], 0.5, v[156:157] op_sel_hi:[1,0,1]
	v_pk_fma_f32 v[158:159], v[122:123], 0.5, v[158:159] op_sel_hi:[1,0,1]
	v_pk_fma_f32 v[160:161], v[116:117], 0.5, v[160:161] op_sel_hi:[1,0,1]
	v_pk_fma_f32 v[162:163], v[118:119], 0.5, v[162:163] op_sel_hi:[1,0,1]
	v_pk_fma_f32 v[164:165], v[156:157], v[156:157], v[164:165]
	v_cvt_pk_bf16_f32 v188, v156, v157
	v_pk_fma_f32 v[164:165], v[158:159], v[158:159], v[164:165]
	v_cvt_pk_bf16_f32 v189, v158, v159
	v_pk_fma_f32 v[164:165], v[160:161], v[160:161], v[164:165]
	v_cvt_pk_bf16_f32 v190, v160, v161
	v_pk_fma_f32 v[164:165], v[162:163], v[162:163], v[164:165]
	v_cvt_pk_bf16_f32 v191, v162, v163
	v_mfma_f32_16x16x32_bf16 v[120:123], v[132:135], v[132:135], 0
	v_mfma_f32_16x16x32_bf16 v[116:119], v[132:135], v[132:135], 0
	s_add_u32 s100, s98, 0x14000
	s_addc_u32 s101, s99, 0
	global_store_dwordx4 v222, v[188:191], s[100:101] offset:2048
	v_add_f32_e32 v171, v164, v165
	s_waitcnt vmcnt(10)
	v_lshlrev_b32_e32 v156, 16, v192
	v_and_b32_e32 v157, 0xffff0000, v192
	v_lshlrev_b32_e32 v158, 16, v193
	v_and_b32_e32 v159, 0xffff0000, v193
	v_lshlrev_b32_e32 v160, 16, v194
	v_and_b32_e32 v161, 0xffff0000, v194
	v_lshlrev_b32_e32 v162, 16, v195
	v_and_b32_e32 v163, 0xffff0000, v195
	v_pk_fma_f32 v[156:157], v[16:17], 0.5, v[156:157] op_sel_hi:[1,0,1]
	v_pk_fma_f32 v[158:159], v[18:19], 0.5, v[158:159] op_sel_hi:[1,0,1]
	v_pk_fma_f32 v[160:161], v[12:13], 0.5, v[160:161] op_sel_hi:[1,0,1]
	v_pk_fma_f32 v[162:163], v[14:15], 0.5, v[162:163] op_sel_hi:[1,0,1]
	v_pk_mul_f32 v[164:165], v[156:157], v[156:157]
	v_cvt_pk_bf16_f32 v192, v156, v157
	v_pk_fma_f32 v[164:165], v[158:159], v[158:159], v[164:165]
	v_cvt_pk_bf16_f32 v193, v158, v159
	v_pk_fma_f32 v[164:165], v[160:161], v[160:161], v[164:165]
	v_cvt_pk_bf16_f32 v194, v160, v161
	v_pk_fma_f32 v[164:165], v[162:163], v[162:163], v[164:165]
	v_cvt_pk_bf16_f32 v195, v162, v163
	v_mfma_f32_16x16x32_bf16 v[16:19], v[132:135], v[132:135], 0
	v_mfma_f32_16x16x32_bf16 v[12:15], v[132:135], v[132:135], 0
	s_add_u32 s100, s98, 0x5000
	s_addc_u32 s101, s99, 0
	global_store_dwordx4 v222, v[192:195], s[100:101]
	s_nop 0
	s_waitcnt vmcnt(9)
; __device__ __forceinline__ unsigned cvt_pk_bf16(float lo, float hi) { unsigned r; asm volatile("v_cvt_pk_bf16_f32 %0, %1, %2" : "=v"(r) : "v"(lo), "v"(hi)); return r; }
;     __device__ __forceinline__ void operator()(f32x4 (&acc)[2][2][4][2], const Unit& u, int wr, int wc, LAS unsigned char* lds, int& rs_pm) const {
;     ...
;             for (int m = 0; m < 4; ++m) { float ss = 0.f;
;                 bf16* const xrow = xb + (((size_t)(u.pm * 32 + u.pn * 4 + (wc >> 1)) * BM + (wr * 64 + fr + ai * HALF + m * 16)) * 64 + (wc & 1) * 32 + 8 * fq);
; #pragma unroll
;                 for (int bj = 0; bj < 2; ++bj) {
;                     const u32x4 xw = *(const u32x4*)(xrow + (size_t)bj * (2 * BM * 64));
;                     const f32x4 x0 = (f32x4){bflo(xw.x), bfhi(xw.x), bflo(xw.y), bfhi(xw.y)}, x1 = (f32x4){bflo(xw.z), bfhi(xw.z), bflo(xw.w), bfhi(xw.w)};
;                     const f32x4 v0 = x0 + acc[ai][bj][m][0] * alpha, v1 = x1 + acc[ai][bj][m][1] * alpha; zero_acc(acc[ai][bj][m][0], zb); zero_acc(acc[ai][bj][m][1], zb);
;                     ss += (v0[0] * v0[0] + v0[1] * v0[1]) + (v0[2] * v0[2] + v0[3] * v0[3]) + (v1[0] * v1[0] + v1[1] * v1[1]) + (v1[2] * v1[2] + v1[3] * v1[3]);
;                     u32x4 w; w.x = cvt_pk_bf16(v0[0], v0[1]); w.y = cvt_pk_bf16(v0[2], v0[3]); w.z = cvt_pk_bf16(v1[0], v1[1]); w.w = cvt_pk_bf16(v1[2], v1[3]);
;                     *(u32x4*)(xrow + (size_t)bj * (2 * BM * 64)) = w; }
;                 ss += __shfl_xor(ss, 16); ss += __shfl_xor(ss, 32);
;                 if (fq == 0) part[(size_t)(row0 + ai * HALF + m * 16) * 32 + u.pn * 4 + wc] = ss;
;                 asm volatile("" ::: "memory"); }
	v_lshlrev_b32_e32 v156, 16, v196
	v_and_b32_e32 v157, 0xffff0000, v196
	v_lshlrev_b32_e32 v158, 16, v197
	v_and_b32_e32 v159, 0xffff0000, v197
	v_lshlrev_b32_e32 v160, 16, v198
	v_and_b32_e32 v161, 0xffff0000, v198
	v_lshlrev_b32_e32 v162, 16, v199
	v_and_b32_e32 v163, 0xffff0000, v199
	v_pk_fma_f32 v[156:157], v[112:113], 0.5, v[156:157] op_sel_hi:[1,0,1]
	v_pk_fma_f32 v[158:159], v[114:115], 0.5, v[158:159] op_sel_hi:[1,0,1]
	v_pk_fma_f32 v[160:161], v[108:109], 0.5, v[160:161] op_sel_hi:[1,0,1]
	v_pk_fma_f32 v[162:163], v[110:111], 0.5, v[162:163] op_sel_hi:[1,0,1]
	v_pk_fma_f32 v[164:165], v[156:157], v[156:157], v[164:165]
	v_cvt_pk_bf16_f32 v196, v156, v157
	v_pk_fma_f32 v[164:165], v[158:159], v[158:159], v[164:165]
	v_cvt_pk_bf16_f32 v197, v158, v159
	v_pk_fma_f32 v[164:165], v[160:161], v[160:161], v[164:165]
	v_cvt_pk_bf16_f32 v198, v160, v161
	v_pk_fma_f32 v[164:165], v[162:163], v[162:163], v[164:165]
	v_cvt_pk_bf16_f32 v199, v162, v163
	v_mfma_f32_16x16x32_bf16 v[112:115], v[132:135], v[132:135], 0
	v_mfma_f32_16x16x32_bf16 v[108:111], v[132:135], v[132:135], 0
	s_add_u32 s100, s98, 0x15000
	s_addc_u32 s101, s99, 0
	global_store_dwordx4 v222, v[196:199], s[100:101]
	v_add_f32_e32 v172, v164, v165
	s_waitcnt vmcnt(8)
	v_lshlrev_b32_e32 v156, 16, v214
	v_and_b32_e32 v157, 0xffff0000, v214
	v_lshlrev_b32_e32 v158, 16, v215
	v_and_b32_e32 v159, 0xffff0000, v215
	v_lshlrev_b32_e32 v160, 16, v216
	v_and_b32_e32 v161, 0xffff0000, v216
	v_lshlrev_b32_e32 v162, 16, v217
	v_and_b32_e32 v163, 0xffff0000, v217
	v_pk_fma_f32 v[156:157], v[60:61], 0.5, v[156:157] op_sel_hi:[1,0,1]
	v_pk_fma_f32 v[158:159], v[62:63], 0.5, v[158:159] op_sel_hi:[1,0,1]
	v_pk_fma_f32 v[160:161], v[68:69], 0.5, v[160:161] op_sel_hi:[1,0,1]
	v_pk_fma_f32 v[162:163], v[70:71], 0.5, v[162:163] op_sel_hi:[1,0,1]
	v_pk_mul_f32 v[164:165], v[156:157], v[156:157]
	v_cvt_pk_bf16_f32 v214, v156, v157
	v_pk_fma_f32 v[164:165], v[158:159], v[158:159], v[164:165]
	v_cvt_pk_bf16_f32 v215, v158, v159
	v_pk_fma_f32 v[164:165], v[160:161], v[160:161], v[164:165]
	v_cvt_pk_bf16_f32 v216, v160, v161
	v_pk_fma_f32 v[164:165], v[162:163], v[162:163], v[164:165]
	v_cvt_pk_bf16_f32 v217, v162, v163
	v_mfma_f32_16x16x32_bf16 v[60:63], v[132:135], v[132:135], 0
	v_mfma_f32_16x16x32_bf16 v[68:71], v[132:135], v[132:135], 0
	s_add_u32 s100, s98, 0x5000
	s_addc_u32 s101, s99, 0
	global_store_dwordx4 v222, v[214:217], s[100:101] offset:2048
	s_nop 0
	s_waitcnt vmcnt(7)
	v_lshlrev_b32_e32 v156, 16, v218
	v_and_b32_e32 v157, 0xffff0000, v218
	v_lshlrev_b32_e32 v158, 16, v219
	v_and_b32_e32 v159, 0xffff0000, v219
	v_lshlrev_b32_e32 v160, 16, v220
	v_and_b32_e32 v161, 0xffff0000, v220
	v_lshlrev_b32_e32 v162, 16, v221
	v_and_b32_e32 v163, 0xffff0000, v221
	v_pk_fma_f32 v[156:157], v[104:105], 0.5, v[156:157] op_sel_hi:[1,0,1]
	v_pk_fma_f32 v[158:159], v[106:107], 0.5, v[158:159] op_sel_hi:[1,0,1]
	v_pk_fma_f32 v[160:161], v[100:101], 0.5, v[160:161] op_sel_hi:[1,0,1]
	v_pk_fma_f32 v[162:163], v[102:103], 0.5, v[162:163] op_sel_hi:[1,0,1]
	v_pk_fma_f32 v[164:165], v[156:157], v[156:157], v[164:165]
	v_cvt_pk_bf16_f32 v218, v156, v157
	v_pk_fma_f32 v[164:165], v[158:159], v[158:159], v[164:165]
	v_cvt_pk_bf16_f32 v219, v158, v159
	v_pk_fma_f32 v[164:165], v[160:161], v[160:161], v[164:165]
	v_cvt_pk_bf16_f32 v220, v160, v161
	v_pk_fma_f32 v[164:165], v[162:163], v[162:163], v[164:165]
	v_cvt_pk_bf16_f32 v221, v162, v163
	v_mfma_f32_16x16x32_bf16 v[104:107], v[132:135], v[132:135], 0
	v_mfma_f32_16x16x32_bf16 v[100:103], v[132:135], v[132:135], 0
	s_add_u32 s100, s98, 0x15000
	s_addc_u32 s101, s99, 0
	global_store_dwordx4 v222, v[218:221], s[100:101] offset:2048
	v_add_f32_e32 v173, v164, v165
	ds_bpermute_b32 v156, v174, v166
	ds_bpermute_b32 v157, v174, v167
	ds_bpermute_b32 v158, v174, v168
	ds_bpermute_b32 v159, v174, v169
	ds_bpermute_b32 v160, v174, v170
	ds_bpermute_b32 v161, v174, v171
	ds_bpermute_b32 v162, v174, v172
	ds_bpermute_b32 v163, v174, v173
	s_waitcnt lgkmcnt(0)
	v_add_f32_e32 v166, v166, v156
	v_add_f32_e32 v167, v167, v157
	v_add_f32_e32 v168, v168, v158
	v_add_f32_e32 v169, v169, v159
	v_add_f32_e32 v170, v170, v160
	v_add_f32_e32 v171, v171, v161
	v_add_f32_e32 v172, v172, v162
	v_add_f32_e32 v173, v173, v163
	ds_bpermute_b32 v156, v175, v166
	ds_bpermute_b32 v157, v175, v167
	ds_bpermute_b32 v158, v175, v168
	ds_bpermute_b32 v159, v175, v169
	ds_bpermute_b32 v160, v175, v170
	ds_bpermute_b32 v161, v175, v171
	ds_bpermute_b32 v162, v175, v172
	ds_bpermute_b32 v163, v175, v173
	s_waitcnt lgkmcnt(0)
	v_add_f32_e32 v166, v166, v156
	v_add_f32_e32 v167, v167, v157
	v_add_f32_e32 v168, v168, v158
	v_add_f32_e32 v169, v169, v159
	v_add_f32_e32 v170, v170, v160
	v_add_f32_e32 v171, v171, v161
	v_add_f32_e32 v172, v172, v162
	v_add_f32_e32 v173, v173, v163
	s_mov_b64 s[34:35], exec
	s_mov_b64 exec, 0xffff
	global_store_dword v222, v166, s[22:23]
	global_store_dword v222, v167, s[22:23] offset:2048
	s_add_u32 s100, s22, 0x1000
	s_addc_u32 s101, s23, 0
	global_store_dword v222, v168, s[100:101]
	s_add_u32 s100, s22, 0x1000
	s_addc_u32 s101, s23, 0
	global_store_dword v222, v169, s[100:101] offset:2048
	s_add_u32 s100, s22, 0x4000
	s_addc_u32 s101, s23, 0
	global_store_dword v222, v170, s[100:101]
	s_add_u32 s100, s22, 0x4000
	s_addc_u32 s101, s23, 0
	global_store_dword v222, v171, s[100:101] offset:2048
	s_add_u32 s100, s22, 0x5000
	s_addc_u32 s101, s23, 0
	global_store_dword v222, v172, s[100:101]
	s_add_u32 s100, s22, 0x5000
	s_addc_u32 s101, s23, 0
	global_store_dword v222, v173, s[100:101] offset:2048
	s_mov_b64 exec, s[34:35]
	s_and_b64 vcc, exec, s[40:41]
	s_mov_b64 s[10:11], -1
	s_cbranch_vccnz .LBB0_286
	s_andn2_b64 vcc, exec, s[18:19]
	s_cbranch_vccnz .LBB0_285
	s_barrier
	s_branch .LBB0_285

; #define LAS __attribute__((address_space(3)))
; __device__ __forceinline__ unsigned cvt_pk_bf16(float lo, float hi) { unsigned r; asm volatile("v_cvt_pk_bf16_f32 %0, %1, %2" : "=v"(r) : "v"(lo), "v"(hi)); return r; }
; __device__ __forceinline__ u32x4 zero_frag() { unsigned z_ = 0u; asm volatile("" : "+v"(z_)); return (u32x4){z_, z_, z_, z_}; }
; __device__ __forceinline__ void epi_lane(int& fr, int& fq) { unsigned ones = ~0u; asm volatile("" : "+s"(ones)); const int ln = (int)__builtin_amdgcn_mbcnt_hi(ones, __builtin_amdgcn_mbcnt_lo(ones, 0u)); fr = ln & 15; fq = ln >> 4; }
;     __device__ __forceinline__ void operator()(f32x4 (&acc)[2][2][4][2], const Unit& u, int wr, int wc, LAS unsigned char* lds, int& rs_pm) const {
;         int fr, fq; epi_lane(fr, fq);
;         const int row0 = u.pm * BM + wr * 64 + fr, col0 = u.pn * BM + wc * 32 + 8 * fq; u32x4 zb = zero_frag();
; #pragma unroll
;         for (int ai = 0; ai < 2; ++ai)
; #pragma unroll
;             for (int m = 0; m < 4; ++m) { float ss = 0.f;
;                 bf16* const xrow = xb + (((size_t)(u.pm * 32 + u.pn * 4 + (wc >> 1)) * BM + (wr * 64 + fr + ai * HALF + m * 16)) * 64 + (wc & 1) * 32 + 8 * fq);
; #pragma unroll
;                 for (int bj = 0; bj < 2; ++bj) {
;                     const u32x4 xw = *(const u32x4*)(xrow + (size_t)bj * (2 * BM * 64));
;                     const f32x4 x0 = (f32x4){bflo(xw.x), bfhi(xw.x), bflo(xw.y), bfhi(xw.y)}, x1 = (f32x4){bflo(xw.z), bfhi(xw.z), bflo(xw.w), bfhi(xw.w)};
;                     const f32x4 v0 = x0 + acc[ai][bj][m][0] * alpha, v1 = x1 + acc[ai][bj][m][1] * alpha; zero_acc(acc[ai][bj][m][0], zb); zero_acc(acc[ai][bj][m][1], zb);
;                     ss += (v0[0] * v0[0] + v0[1] * v0[1]) + (v0[2] * v0[2] + v0[3] * v0[3]) + (v1[0] * v1[0] + v1[1] * v1[1]) + (v1[2] * v1[2] + v1[3] * v1[3]);
;                     u32x4 w; w.x = cvt_pk_bf16(v0[0], v0[1]); w.y = cvt_pk_bf16(v0[2], v0[3]); w.z = cvt_pk_bf16(v1[0], v1[1]); w.w = cvt_pk_bf16(v1[2], v1[3]);
;                     *(u32x4*)(xrow + (size_t)bj * (2 * BM * 64)) = w; }
.LBB0_850:
	v_mov_b32_e32 v132, v1
	v_mov_b32_e32 v133, v1
	v_mov_b32_e32 v134, v1
	v_mov_b32_e32 v135, v1
	v_xor_b32_e32 v174, 16, v238
	v_xor_b32_e32 v175, 32, v238
	v_lshlrev_b32_e32 v174, 2, v174
	v_lshlrev_b32_e32 v175, 2, v175
	s_waitcnt vmcnt(7)
	v_lshlrev_b32_e32 v156, 16, v176
	v_and_b32_e32 v157, 0xffff0000, v176
	v_lshlrev_b32_e32 v158, 16, v177
	v_and_b32_e32 v159, 0xffff0000, v177
	v_lshlrev_b32_e32 v160, 16, v178
	v_and_b32_e32 v161, 0xffff0000, v178
	v_lshlrev_b32_e32 v162, 16, v179
	v_and_b32_e32 v163, 0xffff0000, v179
	v_pk_add_f32 v[156:157], v[8:9], v[156:157]
	v_pk_add_f32 v[158:159], v[10:11], v[158:159]
	v_pk_add_f32 v[160:161], v[56:57], v[160:161]
	v_pk_add_f32 v[162:163], v[58:59], v[162:163]
	v_pk_mul_f32 v[164:165], v[156:157], v[156:157]
	v_cvt_pk_bf16_f32 v176, v156, v157
	v_pk_fma_f32 v[164:165], v[158:159], v[158:159], v[164:165]
	v_cvt_pk_bf16_f32 v177, v158, v159
	v_pk_fma_f32 v[164:165], v[160:161], v[160:161], v[164:165]
	v_cvt_pk_bf16_f32 v178, v160, v161
	v_pk_fma_f32 v[164:165], v[162:163], v[162:163], v[164:165]
	v_cvt_pk_bf16_f32 v179, v162, v163
	v_mfma_f32_16x16x32_bf16 v[8:11], v[132:135], v[132:135], 0
	v_mfma_f32_16x16x32_bf16 v[56:59], v[132:135], v[132:135], 0
	global_store_dwordx4 v222, v[176:179], s[98:99]
	s_nop 0
	s_add_u32 s100, s98, 0x4000
	s_addc_u32 s101, s99, 0
	global_load_dwordx4 v[176:179], v222, s[100:101]
	s_waitcnt vmcnt(8)
	v_lshlrev_b32_e32 v156, 16, v180
	v_and_b32_e32 v157, 0xffff0000, v180
	v_lshlrev_b32_e32 v158, 16, v181
	v_and_b32_e32 v159, 0xffff0000, v181
	v_lshlrev_b32_e32 v160, 16, v182
	v_and_b32_e32 v161, 0xffff0000, v182
	v_lshlrev_b32_e32 v162, 16, v183
	v_and_b32_e32 v163, 0xffff0000, v183
	v_pk_add_f32 v[156:157], v[4:5], v[156:157]
	v_pk_add_f32 v[158:159], v[6:7], v[158:159]
	v_pk_add_f32 v[160:161], v[28:29], v[160:161]
	v_pk_add_f32 v[162:163], v[30:31], v[162:163]
	v_pk_fma_f32 v[164:165], v[156:157], v[156:157], v[164:165]
	v_cvt_pk_bf16_f32 v180, v156, v157
	v_pk_fma_f32 v[164:165], v[158:159], v[158:159], v[164:165]
	v_cvt_pk_bf16_f32 v181, v158, v159
	v_pk_fma_f32 v[164:165], v[160:161], v[160:161], v[164:165]
	v_cvt_pk_bf16_f32 v182, v160, v161
	v_pk_fma_f32 v[164:165], v[162:163], v[162:163], v[164:165]
	v_cvt_pk_bf16_f32 v183, v162, v163
	v_mfma_f32_16x16x32_bf16 v[4:7], v[132:135], v[132:135], 0
	v_mfma_f32_16x16x32_bf16 v[28:31], v[132:135], v[132:135], 0
	s_add_u32 s100, s98, 0x10000
	s_addc_u32 s101, s99, 0
	global_store_dwordx4 v222, v[180:183], s[100:101]
	v_add_f32_e32 v166, v164, v165
	s_add_u32 s100, s98, 0x14000
	s_addc_u32 s101, s99, 0
	global_load_dwordx4 v[180:183], v222, s[100:101]
	s_waitcnt vmcnt(9)
	v_lshlrev_b32_e32 v156, 16, v184
	v_and_b32_e32 v157, 0xffff0000, v184
	v_lshlrev_b32_e32 v158, 16, v185
	v_and_b32_e32 v159, 0xffff0000, v185
	v_lshlrev_b32_e32 v160, 16, v186
	v_and_b32_e32 v161, 0xffff0000, v186
	v_lshlrev_b32_e32 v162, 16, v187
	v_and_b32_e32 v163, 0xffff0000, v187
	v_pk_add_f32 v[156:157], v[52:53], v[156:157]
	v_pk_add_f32 v[158:159], v[54:55], v[158:159]
	v_pk_add_f32 v[160:161], v[48:49], v[160:161]
	v_pk_add_f32 v[162:163], v[50:51], v[162:163]
	v_pk_mul_f32 v[164:165], v[156:157], v[156:157]
	v_cvt_pk_bf16_f32 v184, v156, v157
	v_pk_fma_f32 v[164:165], v[158:159], v[158:159], v[164:165]
	v_cvt_pk_bf16_f32 v185, v158, v159
	v_pk_fma_f32 v[164:165], v[160:161], v[160:161], v[164:165]
	v_cvt_pk_bf16_f32 v186, v160, v161
	v_pk_fma_f32 v[164:165], v[162:163], v[162:163], v[164:165]
	v_cvt_pk_bf16_f32 v187, v162, v163
	v_mfma_f32_16x16x32_bf16 v[52:55], v[132:135], v[132:135], 0
	v_mfma_f32_16x16x32_bf16 v[48:51], v[132:135], v[132:135], 0
	global_store_dwordx4 v222, v[184:187], s[98:99] offset:2048
	s_nop 0
	s_add_u32 s100, s98, 0x4000
	s_addc_u32 s101, s99, 0
	global_load_dwordx4 v[184:187], v222, s[100:101] offset:2048
	s_waitcnt vmcnt(10)
	v_lshlrev_b32_e32 v156, 16, v188
	v_and_b32_e32 v157, 0xffff0000, v188
	v_lshlrev_b32_e32 v158, 16, v189
	v_and_b32_e32 v159, 0xffff0000, v189
	v_lshlrev_b32_e32 v160, 16, v190
	v_and_b32_e32 v161, 0xffff0000, v190
	v_lshlrev_b32_e32 v162, 16, v191
	v_and_b32_e32 v163, 0xffff0000, v191
	v_pk_add_f32 v[156:157], v[96:97], v[156:157]
	v_pk_add_f32 v[158:159], v[98:99], v[158:159]
	v_pk_add_f32 v[160:161], v[92:93], v[160:161]
	v_pk_add_f32 v[162:163], v[94:95], v[162:163]
	v_pk_fma_f32 v[164:165], v[156:157], v[156:157], v[164:165]
	v_cvt_pk_bf16_f32 v188, v156, v157
	v_pk_fma_f32 v[164:165], v[158:159], v[158:159], v[164:165]
	v_cvt_pk_bf16_f32 v189, v158, v159
	v_pk_fma_f32 v[164:165], v[160:161], v[160:161], v[164:165]
	v_cvt_pk_bf16_f32 v190, v160, v161
	v_pk_fma_f32 v[164:165], v[162:163], v[162:163], v[164:165]
	v_cvt_pk_bf16_f32 v191, v162, v163
	v_mfma_f32_16x16x32_bf16 v[96:99], v[132:135], v[132:135], 0
	v_mfma_f32_16x16x32_bf16 v[92:95], v[132:135], v[132:135], 0
	s_add_u32 s100, s98, 0x10000
	s_addc_u32 s101, s99, 0
	global_store_dwordx4 v222, v[188:191], s[100:101] offset:2048
	v_add_f32_e32 v167, v164, v165
	s_add_u32 s100, s98, 0x14000
	s_addc_u32 s101, s99, 0
	global_load_dwordx4 v[188:191], v222, s[100:101] offset:2048
	s_waitcnt vmcnt(11)
; __device__ __forceinline__ unsigned cvt_pk_bf16(float lo, float hi) { unsigned r; asm volatile("v_cvt_pk_bf16_f32 %0, %1, %2" : "=v"(r) : "v"(lo), "v"(hi)); return r; }
;     __device__ __forceinline__ void operator()(f32x4 (&acc)[2][2][4][2], const Unit& u, int wr, int wc, LAS unsigned char* lds, int& rs_pm) const {
;     ...
;                 bf16* const xrow = xb + (((size_t)(u.pm * 32 + u.pn * 4 + (wc >> 1)) * BM + (wr * 64 + fr + ai * HALF + m * 16)) * 64 + (wc & 1) * 32 + 8 * fq);
; #pragma unroll
;                 for (int bj = 0; bj < 2; ++bj) {
;                     const u32x4 xw = *(const u32x4*)(xrow + (size_t)bj * (2 * BM * 64));
;                     const f32x4 x0 = (f32x4){bflo(xw.x), bfhi(xw.x), bflo(xw.y), bfhi(xw.y)}, x1 = (f32x4){bflo(xw.z), bfhi(xw.z), bflo(xw.w), bfhi(xw.w)};
;                     const f32x4 v0 = x0 + acc[ai][bj][m][0] * alpha, v1 = x1 + acc[ai][bj][m][1] * alpha; zero_acc(acc[ai][bj][m][0], zb); zero_acc(acc[ai][bj][m][1], zb);
;                     ss += (v0[0] * v0[0] + v0[1] * v0[1]) + (v0[2] * v0[2] + v0[3] * v0[3]) + (v1[0] * v1[0] + v1[1] * v1[1]) + (v1[2] * v1[2] + v1[3] * v1[3]);
;                     u32x4 w; w.x = cvt_pk_bf16(v0[0], v0[1]); w.y = cvt_pk_bf16(v0[2], v0[3]); w.z = cvt_pk_bf16(v1[0], v1[1]); w.w = cvt_pk_bf16(v1[2], v1[3]);
;                     *(u32x4*)(xrow + (size_t)bj * (2 * BM * 64)) = w; }
	v_lshlrev_b32_e32 v156, 16, v192
	v_and_b32_e32 v157, 0xffff0000, v192
	v_lshlrev_b32_e32 v158, 16, v193
	v_and_b32_e32 v159, 0xffff0000, v193
	v_lshlrev_b32_e32 v160, 16, v194
	v_and_b32_e32 v161, 0xffff0000, v194
	v_lshlrev_b32_e32 v162, 16, v195
	v_and_b32_e32 v163, 0xffff0000, v195
	v_pk_add_f32 v[156:157], v[44:45], v[156:157]
	v_pk_add_f32 v[158:159], v[46:47], v[158:159]
	v_pk_add_f32 v[160:161], v[40:41], v[160:161]
	v_pk_add_f32 v[162:163], v[42:43], v[162:163]
	v_pk_mul_f32 v[164:165], v[156:157], v[156:157]
	v_cvt_pk_bf16_f32 v192, v156, v157
	v_pk_fma_f32 v[164:165], v[158:159], v[158:159], v[164:165]
	v_cvt_pk_bf16_f32 v193, v158, v159
	v_pk_fma_f32 v[164:165], v[160:161], v[160:161], v[164:165]
	v_cvt_pk_bf16_f32 v194, v160, v161
	v_pk_fma_f32 v[164:165], v[162:163], v[162:163], v[164:165]
	v_cvt_pk_bf16_f32 v195, v162, v163
	v_mfma_f32_16x16x32_bf16 v[44:47], v[132:135], v[132:135], 0
	v_mfma_f32_16x16x32_bf16 v[40:43], v[132:135], v[132:135], 0
	s_add_u32 s100, s98, 0x1000
	s_addc_u32 s101, s99, 0
	global_store_dwordx4 v222, v[192:195], s[100:101]
	s_nop 0
	s_add_u32 s100, s98, 0x5000
	s_addc_u32 s101, s99, 0
	global_load_dwordx4 v[192:195], v222, s[100:101]
	s_waitcnt vmcnt(12)
	v_lshlrev_b32_e32 v156, 16, v196
	v_and_b32_e32 v157, 0xffff0000, v196
	v_lshlrev_b32_e32 v158, 16, v197
	v_and_b32_e32 v159, 0xffff0000, v197
	v_lshlrev_b32_e32 v160, 16, v198
	v_and_b32_e32 v161, 0xffff0000, v198
	v_lshlrev_b32_e32 v162, 16, v199
	v_and_b32_e32 v163, 0xffff0000, v199
	v_pk_add_f32 v[156:157], v[88:89], v[156:157]
	v_pk_add_f32 v[158:159], v[90:91], v[158:159]
	v_pk_add_f32 v[160:161], v[84:85], v[160:161]
	v_pk_add_f32 v[162:163], v[86:87], v[162:163]
	v_pk_fma_f32 v[164:165], v[156:157], v[156:157], v[164:165]
	v_cvt_pk_bf16_f32 v196, v156, v157
	v_pk_fma_f32 v[164:165], v[158:159], v[158:159], v[164:165]
	v_cvt_pk_bf16_f32 v197, v158, v159
	v_pk_fma_f32 v[164:165], v[160:161], v[160:161], v[164:165]
	v_cvt_pk_bf16_f32 v198, v160, v161
	v_pk_fma_f32 v[164:165], v[162:163], v[162:163], v[164:165]
	v_cvt_pk_bf16_f32 v199, v162, v163
	v_mfma_f32_16x16x32_bf16 v[88:91], v[132:135], v[132:135], 0
	v_mfma_f32_16x16x32_bf16 v[84:87], v[132:135], v[132:135], 0
	s_add_u32 s100, s98, 0x11000
	s_addc_u32 s101, s99, 0
	global_store_dwordx4 v222, v[196:199], s[100:101]
	v_add_f32_e32 v168, v164, v165
	s_add_u32 s100, s98, 0x15000
	s_addc_u32 s101, s99, 0
	global_load_dwordx4 v[196:199], v222, s[100:101]
	s_waitcnt vmcnt(13)
	v_lshlrev_b32_e32 v156, 16, v214
	v_and_b32_e32 v157, 0xffff0000, v214
	v_lshlrev_b32_e32 v158, 16, v215
	v_and_b32_e32 v159, 0xffff0000, v215
	v_lshlrev_b32_e32 v160, 16, v216
	v_and_b32_e32 v161, 0xffff0000, v216
	v_lshlrev_b32_e32 v162, 16, v217
	v_and_b32_e32 v163, 0xffff0000, v217
	v_pk_add_f32 v[156:157], v[36:37], v[156:157]
	v_pk_add_f32 v[158:159], v[38:39], v[158:159]
	v_pk_add_f32 v[160:161], v[32:33], v[160:161]
	v_pk_add_f32 v[162:163], v[34:35], v[162:163]
	v_pk_mul_f32 v[164:165], v[156:157], v[156:157]
	v_cvt_pk_bf16_f32 v214, v156, v157
	v_pk_fma_f32 v[164:165], v[158:159], v[158:159], v[164:165]
	v_cvt_pk_bf16_f32 v215, v158, v159
	v_pk_fma_f32 v[164:165], v[160:161], v[160:161], v[164:165]
	v_cvt_pk_bf16_f32 v216, v160, v161
	v_pk_fma_f32 v[164:165], v[162:163], v[162:163], v[164:165]
	v_cvt_pk_bf16_f32 v217, v162, v163
	v_mfma_f32_16x16x32_bf16 v[36:39], v[132:135], v[132:135], 0
	v_mfma_f32_16x16x32_bf16 v[32:35], v[132:135], v[132:135], 0
	s_add_u32 s100, s98, 0x1000
	s_addc_u32 s101, s99, 0
	global_store_dwordx4 v222, v[214:217], s[100:101] offset:2048
	s_nop 0
	s_add_u32 s100, s98, 0x5000
	s_addc_u32 s101, s99, 0
	global_load_dwordx4 v[214:217], v222, s[100:101] offset:2048
	s_waitcnt vmcnt(14)
	v_lshlrev_b32_e32 v156, 16, v218
	v_and_b32_e32 v157, 0xffff0000, v218
	v_lshlrev_b32_e32 v158, 16, v219
	v_and_b32_e32 v159, 0xffff0000, v219
	v_lshlrev_b32_e32 v160, 16, v220
	v_and_b32_e32 v161, 0xffff0000, v220
	v_lshlrev_b32_e32 v162, 16, v221
	v_and_b32_e32 v163, 0xffff0000, v221
	v_pk_add_f32 v[156:157], v[80:81], v[156:157]
	v_pk_add_f32 v[158:159], v[82:83], v[158:159]
	v_pk_add_f32 v[160:161], v[76:77], v[160:161]
	v_pk_add_f32 v[162:163], v[78:79], v[162:163]
	v_pk_fma_f32 v[164:165], v[156:157], v[156:157], v[164:165]
	v_cvt_pk_bf16_f32 v218, v156, v157
	v_pk_fma_f32 v[164:165], v[158:159], v[158:159], v[164:165]
	v_cvt_pk_bf16_f32 v219, v158, v159
	v_pk_fma_f32 v[164:165], v[160:161], v[160:161], v[164:165]
	v_cvt_pk_bf16_f32 v220, v160, v161
	v_pk_fma_f32 v[164:165], v[162:163], v[162:163], v[164:165]
	v_cvt_pk_bf16_f32 v221, v162, v163
	v_mfma_f32_16x16x32_bf16 v[80:83], v[132:135], v[132:135], 0
	v_mfma_f32_16x16x32_bf16 v[76:79], v[132:135], v[132:135], 0
	s_add_u32 s100, s98, 0x11000
	s_addc_u32 s101, s99, 0
	global_store_dwordx4 v222, v[218:221], s[100:101] offset:2048
	v_add_f32_e32 v169, v164, v165
	s_add_u32 s100, s98, 0x15000
	s_addc_u32 s101, s99, 0
	global_load_dwordx4 v[218:221], v222, s[100:101] offset:2048
	s_waitcnt vmcnt(14)
	v_lshlrev_b32_e32 v156, 16, v176
	v_and_b32_e32 v157, 0xffff0000, v176
	v_lshlrev_b32_e32 v158, 16, v177
	v_and_b32_e32 v159, 0xffff0000, v177
	v_lshlrev_b32_e32 v160, 16, v178
	v_and_b32_e32 v161, 0xffff0000, v178
	v_lshlrev_b32_e32 v162, 16, v179
	v_and_b32_e32 v163, 0xffff0000, v179
	v_pk_add_f32 v[156:157], v[24:25], v[156:157]
	v_pk_add_f32 v[158:159], v[26:27], v[158:159]
	v_pk_add_f32 v[160:161], v[20:21], v[160:161]
	v_pk_add_f32 v[162:163], v[22:23], v[162:163]
	v_pk_mul_f32 v[164:165], v[156:157], v[156:157]
	v_cvt_pk_bf16_f32 v176, v156, v157
	v_pk_fma_f32 v[164:165], v[158:159], v[158:159], v[164:165]
	v_cvt_pk_bf16_f32 v177, v158, v159
	v_pk_fma_f32 v[164:165], v[160:161], v[160:161], v[164:165]
	v_cvt_pk_bf16_f32 v178, v160, v161
	v_pk_fma_f32 v[164:165], v[162:163], v[162:163], v[164:165]
	v_cvt_pk_bf16_f32 v179, v162, v163
	v_mfma_f32_16x16x32_bf16 v[24:27], v[132:135], v[132:135], 0
	v_mfma_f32_16x16x32_bf16 v[20:23], v[132:135], v[132:135], 0
	s_add_u32 s100, s98, 0x4000
	s_addc_u32 s101, s99, 0
	global_store_dwordx4 v222, v[176:179], s[100:101]
	s_nop 0
	s_waitcnt vmcnt(13)
; __device__ __forceinline__ unsigned cvt_pk_bf16(float lo, float hi) { unsigned r; asm volatile("v_cvt_pk_bf16_f32 %0, %1, %2" : "=v"(r) : "v"(lo), "v"(hi)); return r; }
;     __device__ __forceinline__ void operator()(f32x4 (&acc)[2][2][4][2], const Unit& u, int wr, int wc, LAS unsigned char* lds, int& rs_pm) const {
;     ...
;                 bf16* const xrow = xb + (((size_t)(u.pm * 32 + u.pn * 4 + (wc >> 1)) * BM + (wr * 64 + fr + ai * HALF + m * 16)) * 64 + (wc & 1) * 32 + 8 * fq);
; #pragma unroll
;                 for (int bj = 0; bj < 2; ++bj) {
;                     const u32x4 xw = *(const u32x4*)(xrow + (size_t)bj * (2 * BM * 64));
;                     const f32x4 x0 = (f32x4){bflo(xw.x), bfhi(xw.x), bflo(xw.y), bfhi(xw.y)}, x1 = (f32x4){bflo(xw.z), bfhi(xw.z), bflo(xw.w), bfhi(xw.w)};
;                     const f32x4 v0 = x0 + acc[ai][bj][m][0] * alpha, v1 = x1 + acc[ai][bj][m][1] * alpha; zero_acc(acc[ai][bj][m][0], zb); zero_acc(acc[ai][bj][m][1], zb);
;                     ss += (v0[0] * v0[0] + v0[1] * v0[1]) + (v0[2] * v0[2] + v0[3] * v0[3]) + (v1[0] * v1[0] + v1[1] * v1[1]) + (v1[2] * v1[2] + v1[3] * v1[3]);
;                     u32x4 w; w.x = cvt_pk_bf16(v0[0], v0[1]); w.y = cvt_pk_bf16(v0[2], v0[3]); w.z = cvt_pk_bf16(v1[0], v1[1]); w.w = cvt_pk_bf16(v1[2], v1[3]);
;                     *(u32x4*)(xrow + (size_t)bj * (2 * BM * 64)) = w; }
	v_lshlrev_b32_e32 v156, 16, v180
	v_and_b32_e32 v157, 0xffff0000, v180
	v_lshlrev_b32_e32 v158, 16, v181
	v_and_b32_e32 v159, 0xffff0000, v181
	v_lshlrev_b32_e32 v160, 16, v182
	v_and_b32_e32 v161, 0xffff0000, v182
	v_lshlrev_b32_e32 v162, 16, v183
	v_and_b32_e32 v163, 0xffff0000, v183
	v_pk_add_f32 v[156:157], v[128:129], v[156:157]
	v_pk_add_f32 v[158:159], v[130:131], v[158:159]
	v_pk_add_f32 v[160:161], v[124:125], v[160:161]
	v_pk_add_f32 v[162:163], v[126:127], v[162:163]
	v_pk_fma_f32 v[164:165], v[156:157], v[156:157], v[164:165]
	v_cvt_pk_bf16_f32 v180, v156, v157
	v_pk_fma_f32 v[164:165], v[158:159], v[158:159], v[164:165]
	v_cvt_pk_bf16_f32 v181, v158, v159
	v_pk_fma_f32 v[164:165], v[160:161], v[160:161], v[164:165]
	v_cvt_pk_bf16_f32 v182, v160, v161
	v_pk_fma_f32 v[164:165], v[162:163], v[162:163], v[164:165]
	v_cvt_pk_bf16_f32 v183, v162, v163
	v_mfma_f32_16x16x32_bf16 v[128:131], v[132:135], v[132:135], 0
	v_mfma_f32_16x16x32_bf16 v[124:127], v[132:135], v[132:135], 0
	s_add_u32 s100, s98, 0x14000
	s_addc_u32 s101, s99, 0
	global_store_dwordx4 v222, v[180:183], s[100:101]
	v_add_f32_e32 v170, v164, v165
	s_waitcnt vmcnt(12)
	v_lshlrev_b32_e32 v156, 16, v184
	v_and_b32_e32 v157, 0xffff0000, v184
	v_lshlrev_b32_e32 v158, 16, v185
	v_and_b32_e32 v159, 0xffff0000, v185
	v_lshlrev_b32_e32 v160, 16, v186
	v_and_b32_e32 v161, 0xffff0000, v186
	v_lshlrev_b32_e32 v162, 16, v187
	v_and_b32_e32 v163, 0xffff0000, v187
	v_pk_add_f32 v[156:157], v[64:65], v[156:157]
	v_pk_add_f32 v[158:159], v[66:67], v[158:159]
	v_pk_add_f32 v[160:161], v[72:73], v[160:161]
	v_pk_add_f32 v[162:163], v[74:75], v[162:163]
	v_pk_mul_f32 v[164:165], v[156:157], v[156:157]
	v_cvt_pk_bf16_f32 v184, v156, v157
	v_pk_fma_f32 v[164:165], v[158:159], v[158:159], v[164:165]
	v_cvt_pk_bf16_f32 v185, v158, v159
	v_pk_fma_f32 v[164:165], v[160:161], v[160:161], v[164:165]
	v_cvt_pk_bf16_f32 v186, v160, v161
	v_pk_fma_f32 v[164:165], v[162:163], v[162:163], v[164:165]
	v_cvt_pk_bf16_f32 v187, v162, v163
	v_mfma_f32_16x16x32_bf16 v[64:67], v[132:135], v[132:135], 0
	v_mfma_f32_16x16x32_bf16 v[72:75], v[132:135], v[132:135], 0
	s_add_u32 s100, s98, 0x4000
	s_addc_u32 s101, s99, 0
	global_store_dwordx4 v222, v[184:187], s[100:101] offset:2048
	s_nop 0
	s_waitcnt vmcnt(11)
	v_lshlrev_b32_e32 v156, 16, v188
	v_and_b32_e32 v157, 0xffff0000, v188
	v_lshlrev_b32_e32 v158, 16, v189
	v_and_b32_e32 v159, 0xffff0000, v189
	v_lshlrev_b32_e32 v160, 16, v190
	v_and_b32_e32 v161, 0xffff0000, v190
	v_lshlrev_b32_e32 v162, 16, v191
	v_and_b32_e32 v163, 0xffff0000, v191
	v_pk_add_f32 v[156:157], v[120:121], v[156:157]
	v_pk_add_f32 v[158:159], v[122:123], v[158:159]
	v_pk_add_f32 v[160:161], v[116:117], v[160:161]
	v_pk_add_f32 v[162:163], v[118:119], v[162:163]
	v_pk_fma_f32 v[164:165], v[156:157], v[156:157], v[164:165]
	v_cvt_pk_bf16_f32 v188, v156, v157
	v_pk_fma_f32 v[164:165], v[158:159], v[158:159], v[164:165]
	v_cvt_pk_bf16_f32 v189, v158, v159
	v_pk_fma_f32 v[164:165], v[160:161], v[160:161], v[164:165]
	v_cvt_pk_bf16_f32 v190, v160, v161
	v_pk_fma_f32 v[164:165], v[162:163], v[162:163], v[164:165]
	v_cvt_pk_bf16_f32 v191, v162, v163
	v_mfma_f32_16x16x32_bf16 v[120:123], v[132:135], v[132:135], 0
	v_mfma_f32_16x16x32_bf16 v[116:119], v[132:135], v[132:135], 0
	s_add_u32 s100, s98, 0x14000
	s_addc_u32 s101, s99, 0
	global_store_dwordx4 v222, v[188:191], s[100:101] offset:2048
	v_add_f32_e32 v171, v164, v165
	s_waitcnt vmcnt(10)
	v_lshlrev_b32_e32 v156, 16, v192
	v_and_b32_e32 v157, 0xffff0000, v192
	v_lshlrev_b32_e32 v158, 16, v193
	v_and_b32_e32 v159, 0xffff0000, v193
	v_lshlrev_b32_e32 v160, 16, v194
	v_and_b32_e32 v161, 0xffff0000, v194
	v_lshlrev_b32_e32 v162, 16, v195
	v_and_b32_e32 v163, 0xffff0000, v195
	v_pk_add_f32 v[156:157], v[16:17], v[156:157]
	v_pk_add_f32 v[158:159], v[18:19], v[158:159]
	v_pk_add_f32 v[160:161], v[12:13], v[160:161]
	v_pk_add_f32 v[162:163], v[14:15], v[162:163]
	v_pk_mul_f32 v[164:165], v[156:157], v[156:157]
	v_cvt_pk_bf16_f32 v192, v156, v157
	v_pk_fma_f32 v[164:165], v[158:159], v[158:159], v[164:165]
	v_cvt_pk_bf16_f32 v193, v158, v159
	v_pk_fma_f32 v[164:165], v[160:161], v[160:161], v[164:165]
	v_cvt_pk_bf16_f32 v194, v160, v161
	v_pk_fma_f32 v[164:165], v[162:163], v[162:163], v[164:165]
	v_cvt_pk_bf16_f32 v195, v162, v163
	v_mfma_f32_16x16x32_bf16 v[16:19], v[132:135], v[132:135], 0
	v_mfma_f32_16x16x32_bf16 v[12:15], v[132:135], v[132:135], 0
	s_add_u32 s100, s98, 0x5000
	s_addc_u32 s101, s99, 0
	global_store_dwordx4 v222, v[192:195], s[100:101]
	s_nop 0
	s_waitcnt vmcnt(9)
; __device__ __forceinline__ unsigned cvt_pk_bf16(float lo, float hi) { unsigned r; asm volatile("v_cvt_pk_bf16_f32 %0, %1, %2" : "=v"(r) : "v"(lo), "v"(hi)); return r; }
; #define PG8_BAR __builtin_amdgcn_s_barrier()
; template <class Epi, bool ALIGN_EPI>
; __device__ __forceinline__ void gemm_phase(LAS unsigned char* lds, const Gemm g, const StaticOrder& S, const Epi& E, const int tid) {
;     ...
;         if constexpr (ALIGN_EPI) { if (wr == 0) PG8_BAR; }
;         E(acc, cur, wr, wc, lds, rs_pm);
;         if (!has_next) break;
;         cur = nxt; cA = nA; cB = nB; ++ui;
;         if constexpr (ALIGN_EPI) { if (wr == 1) PG8_BAR; }
;     __device__ __forceinline__ void operator()(f32x4 (&acc)[2][2][4][2], const Unit& u, int wr, int wc, LAS unsigned char* lds, int& rs_pm) const {
;     ...
;                 for (int bj = 0; bj < 2; ++bj) {
;                     const u32x4 xw = *(const u32x4*)(xrow + (size_t)bj * (2 * BM * 64));
;                     const f32x4 x0 = (f32x4){bflo(xw.x), bfhi(xw.x), bflo(xw.y), bfhi(xw.y)}, x1 = (f32x4){bflo(xw.z), bfhi(xw.z), bflo(xw.w), bfhi(xw.w)};
;                     const f32x4 v0 = x0 + acc[ai][bj][m][0] * alpha, v1 = x1 + acc[ai][bj][m][1] * alpha; zero_acc(acc[ai][bj][m][0], zb); zero_acc(acc[ai][bj][m][1], zb);
;                     ss += (v0[0] * v0[0] + v0[1] * v0[1]) + (v0[2] * v0[2] + v0[3] * v0[3]) + (v1[0] * v1[0] + v1[1] * v1[1]) + (v1[2] * v1[2] + v1[3] * v1[3]);
;                     u32x4 w; w.x = cvt_pk_bf16(v0[0], v0[1]); w.y = cvt_pk_bf16(v0[2], v0[3]); w.z = cvt_pk_bf16(v1[0], v1[1]); w.w = cvt_pk_bf16(v1[2], v1[3]);
;                     *(u32x4*)(xrow + (size_t)bj * (2 * BM * 64)) = w; }
;                 ss += __shfl_xor(ss, 16); ss += __shfl_xor(ss, 32);
;                 if (fq == 0) part[(size_t)(row0 + ai * HALF + m * 16) * 32 + u.pn * 4 + wc] = ss;
	v_lshlrev_b32_e32 v156, 16, v196
	v_and_b32_e32 v157, 0xffff0000, v196
	v_lshlrev_b32_e32 v158, 16, v197
	v_and_b32_e32 v159, 0xffff0000, v197
	v_lshlrev_b32_e32 v160, 16, v198
	v_and_b32_e32 v161, 0xffff0000, v198
	v_lshlrev_b32_e32 v162, 16, v199
	v_and_b32_e32 v163, 0xffff0000, v199
	v_pk_add_f32 v[156:157], v[112:113], v[156:157]
	v_pk_add_f32 v[158:159], v[114:115], v[158:159]
	v_pk_add_f32 v[160:161], v[108:109], v[160:161]
	v_pk_add_f32 v[162:163], v[110:111], v[162:163]
	v_pk_fma_f32 v[164:165], v[156:157], v[156:157], v[164:165]
	v_cvt_pk_bf16_f32 v196, v156, v157
	v_pk_fma_f32 v[164:165], v[158:159], v[158:159], v[164:165]
	v_cvt_pk_bf16_f32 v197, v158, v159
	v_pk_fma_f32 v[164:165], v[160:161], v[160:161], v[164:165]
	v_cvt_pk_bf16_f32 v198, v160, v161
	v_pk_fma_f32 v[164:165], v[162:163], v[162:163], v[164:165]
	v_cvt_pk_bf16_f32 v199, v162, v163
	v_mfma_f32_16x16x32_bf16 v[112:115], v[132:135], v[132:135], 0
	v_mfma_f32_16x16x32_bf16 v[108:111], v[132:135], v[132:135], 0
	s_add_u32 s100, s98, 0x15000
	s_addc_u32 s101, s99, 0
	global_store_dwordx4 v222, v[196:199], s[100:101]
	v_add_f32_e32 v172, v164, v165
	s_waitcnt vmcnt(8)
	v_lshlrev_b32_e32 v156, 16, v214
	v_and_b32_e32 v157, 0xffff0000, v214
	v_lshlrev_b32_e32 v158, 16, v215
	v_and_b32_e32 v159, 0xffff0000, v215
	v_lshlrev_b32_e32 v160, 16, v216
	v_and_b32_e32 v161, 0xffff0000, v216
	v_lshlrev_b32_e32 v162, 16, v217
	v_and_b32_e32 v163, 0xffff0000, v217
	v_pk_add_f32 v[156:157], v[60:61], v[156:157]
	v_pk_add_f32 v[158:159], v[62:63], v[158:159]
	v_pk_add_f32 v[160:161], v[68:69], v[160:161]
	v_pk_add_f32 v[162:163], v[70:71], v[162:163]
	v_pk_mul_f32 v[164:165], v[156:157], v[156:157]
	v_cvt_pk_bf16_f32 v214, v156, v157
	v_pk_fma_f32 v[164:165], v[158:159], v[158:159], v[164:165]
	v_cvt_pk_bf16_f32 v215, v158, v159
	v_pk_fma_f32 v[164:165], v[160:161], v[160:161], v[164:165]
	v_cvt_pk_bf16_f32 v216, v160, v161
	v_pk_fma_f32 v[164:165], v[162:163], v[162:163], v[164:165]
	v_cvt_pk_bf16_f32 v217, v162, v163
	v_mfma_f32_16x16x32_bf16 v[60:63], v[132:135], v[132:135], 0
	v_mfma_f32_16x16x32_bf16 v[68:71], v[132:135], v[132:135], 0
	s_add_u32 s100, s98, 0x5000
	s_addc_u32 s101, s99, 0
	global_store_dwordx4 v222, v[214:217], s[100:101] offset:2048
	s_nop 0
	s_waitcnt vmcnt(7)
	v_lshlrev_b32_e32 v156, 16, v218
	v_and_b32_e32 v157, 0xffff0000, v218
	v_lshlrev_b32_e32 v158, 16, v219
	v_and_b32_e32 v159, 0xffff0000, v219
	v_lshlrev_b32_e32 v160, 16, v220
	v_and_b32_e32 v161, 0xffff0000, v220
	v_lshlrev_b32_e32 v162, 16, v221
	v_and_b32_e32 v163, 0xffff0000, v221
	v_pk_add_f32 v[156:157], v[104:105], v[156:157]
	v_pk_add_f32 v[158:159], v[106:107], v[158:159]
	v_pk_add_f32 v[160:161], v[100:101], v[160:161]
	v_pk_add_f32 v[162:163], v[102:103], v[162:163]
	v_pk_fma_f32 v[164:165], v[156:157], v[156:157], v[164:165]
	v_cvt_pk_bf16_f32 v218, v156, v157
	v_pk_fma_f32 v[164:165], v[158:159], v[158:159], v[164:165]
	v_cvt_pk_bf16_f32 v219, v158, v159
	v_pk_fma_f32 v[164:165], v[160:161], v[160:161], v[164:165]
	v_cvt_pk_bf16_f32 v220, v160, v161
	v_pk_fma_f32 v[164:165], v[162:163], v[162:163], v[164:165]
	v_cvt_pk_bf16_f32 v221, v162, v163
	v_mfma_f32_16x16x32_bf16 v[104:107], v[132:135], v[132:135], 0
	v_mfma_f32_16x16x32_bf16 v[100:103], v[132:135], v[132:135], 0
	s_add_u32 s100, s98, 0x15000
	s_addc_u32 s101, s99, 0
	global_store_dwordx4 v222, v[218:221], s[100:101] offset:2048
	v_add_f32_e32 v173, v164, v165
	ds_bpermute_b32 v156, v174, v166
	ds_bpermute_b32 v157, v174, v167
	ds_bpermute_b32 v158, v174, v168
	ds_bpermute_b32 v159, v174, v169
	ds_bpermute_b32 v160, v174, v170
	ds_bpermute_b32 v161, v174, v171
	ds_bpermute_b32 v162, v174, v172
	ds_bpermute_b32 v163, v174, v173
	s_waitcnt lgkmcnt(0)
	v_add_f32_e32 v166, v166, v156
	v_add_f32_e32 v167, v167, v157
	v_add_f32_e32 v168, v168, v158
	v_add_f32_e32 v169, v169, v159
	v_add_f32_e32 v170, v170, v160
	v_add_f32_e32 v171, v171, v161
	v_add_f32_e32 v172, v172, v162
	v_add_f32_e32 v173, v173, v163
	ds_bpermute_b32 v156, v175, v166
	ds_bpermute_b32 v157, v175, v167
	ds_bpermute_b32 v158, v175, v168
	ds_bpermute_b32 v159, v175, v169
	ds_bpermute_b32 v160, v175, v170
	ds_bpermute_b32 v161, v175, v171
	ds_bpermute_b32 v162, v175, v172
	ds_bpermute_b32 v163, v175, v173
	s_waitcnt lgkmcnt(0)
	v_add_f32_e32 v166, v166, v156
	v_add_f32_e32 v167, v167, v157
	v_add_f32_e32 v168, v168, v158
	v_add_f32_e32 v169, v169, v159
	v_add_f32_e32 v170, v170, v160
	v_add_f32_e32 v171, v171, v161
	v_add_f32_e32 v172, v172, v162
	v_add_f32_e32 v173, v173, v163
	s_mov_b64 s[34:35], exec
	s_mov_b64 exec, 0xffff
	global_store_dword v222, v166, s[22:23]
	global_store_dword v222, v167, s[22:23] offset:2048
	s_add_u32 s100, s22, 0x1000
	s_addc_u32 s101, s23, 0
	global_store_dword v222, v168, s[100:101]
	s_add_u32 s100, s22, 0x1000
	s_addc_u32 s101, s23, 0
	global_store_dword v222, v169, s[100:101] offset:2048
	s_add_u32 s100, s22, 0x4000
	s_addc_u32 s101, s23, 0
	global_store_dword v222, v170, s[100:101]
	s_add_u32 s100, s22, 0x4000
	s_addc_u32 s101, s23, 0
	global_store_dword v222, v171, s[100:101] offset:2048
	s_add_u32 s100, s22, 0x5000
	s_addc_u32 s101, s23, 0
	global_store_dword v222, v172, s[100:101]
	s_add_u32 s100, s22, 0x5000
	s_addc_u32 s101, s23, 0
	global_store_dword v222, v173, s[100:101] offset:2048
	s_mov_b64 exec, s[34:35]
	s_andn2_b64 vcc, exec, s[38:39]
	s_mov_b64 s[10:11], -1
	s_cbranch_vccnz .LBB0_843
	s_andn2_b64 vcc, exec, s[18:19]
	s_cbranch_vccnz .LBB0_842
	s_barrier
	s_branch .LBB0_842
